# ffn2 K-rotation with 128B per m-tile skew (krot sh7)
# speedup vs baseline: 1.0065x; 1.0065x over previous
.LBB0_126:
	s_lshr_b32 s15, s14, 3
	v_mov_b32_e32 v6, v254
	s_and_b32 s16, s15, 0xffffff8
	s_and_b32 s15, s14, 7
	v_ashrrev_i32_e32 v0, 3, v6
	s_lshl_b32 s83, s16, 7
	s_lshl_b32 s14, s14, 4
	v_xor_b32_e32 v5, v0, v6
	s_sub_i32 s14, s14, s83
	v_lshlrev_b32_e32 v1, 3, v5
	s_and_b32 s22, s14, 0xffffff80
	v_and_b32_e32 v7, 56, v1
	v_ashrrev_i32_e32 v1, 31, v0
	s_or_b32 s17, s16, s15
	s_ashr_i32 s23, s22, 31
	v_lshlrev_b64 v[2:3], 12, v[0:1]
	s_lshl_b32 s26, s17, 7
	s_lshl_b64 s[36:37], s[22:23], 13
	s_mov_b64 s[16:17], -1
	s_and_b64 vcc, exec, s[40:41]
	v_lshlrev_b64 v[2:3], 1, v[2:3]
	v_lshlrev_b32_e32 v148, 1, v7
	v_lshlrev_b32_e32 v7, 4, v6
	s_cbranch_vccz .LBB0_128
	s_lshl_b64 s[16:17], s[26:27], 13
	s_add_u32 s16, s25, s16
	s_addc_u32 s17, s33, s17
	s_lshl_b32 s14, s26, 0
	s_and_b32 s14, s14, 0x380
	s_add_u32 s16, s16, s14
	s_addc_u32 s17, s17, 0
	v_lshlrev_b32_e32 v85, 4, v6
	s_add_u32 s40, s44, s36
	v_lshl_add_u64 v[8:9], s[16:17], 0, v[2:3]
	v_readfirstlane_b32 s14, v85
	v_add_u32_e32 v14, 0x1000, v85
	s_addc_u32 s41, s45, s37
	s_lshl_b32 s84, s26, 0
	s_and_b32 s84, s84, 0x380
	s_add_u32 s40, s40, s84
	s_addc_u32 s41, s41, 0
	v_lshl_add_u64 v[8:9], v[8:9], 0, v[148:149]
	s_mov_b32 m0, s14
	s_mov_b64 s[16:17], 0x40000
	v_readfirstlane_b32 s14, v14
	v_add_u32_e32 v14, 0x2000, v85
	v_lshl_add_u64 v[10:11], s[40:41], 0, v[2:3]
	s_barrier
	global_load_lds_dwordx4 v[8:9], off
	v_lshl_add_u64 v[12:13], v[8:9], 0, s[16:17]
	s_mov_b32 m0, s14
	s_mov_b64 s[40:41], 0x80000
	v_readfirstlane_b32 s14, v14
	global_load_lds_dwordx4 v[12:13], off
	v_lshl_add_u64 v[12:13], v[8:9], 0, s[40:41]
	s_mov_b32 m0, s14
	s_mov_b64 s[84:85], 0xc0000
	global_load_lds_dwordx4 v[12:13], off
	v_add_u32_e32 v12, 0x3000, v85
	v_lshl_add_u64 v[8:9], v[8:9], 0, s[84:85]
	v_readfirstlane_b32 s14, v12
	s_mov_b32 m0, s14
	v_add_u32_e32 v12, 0x5000, v85
	global_load_lds_dwordx4 v[8:9], off
	v_add_u32_e32 v8, 0x4000, v85
	v_lshl_add_u64 v[10:11], v[10:11], 0, v[148:149]
	v_readfirstlane_b32 s14, v8
	s_mov_b32 m0, s14
	v_readfirstlane_b32 s14, v12
	v_add_u32_e32 v12, 0x6000, v85
	global_load_lds_dwordx4 v[10:11], off
	v_lshl_add_u64 v[8:9], v[10:11], 0, s[16:17]
	s_mov_b32 m0, s14
	v_readfirstlane_b32 s14, v12
	global_load_lds_dwordx4 v[8:9], off
	v_lshl_add_u64 v[8:9], v[10:11], 0, s[40:41]
	s_mov_b32 m0, s14
	s_mov_b64 s[16:17], 0
	global_load_lds_dwordx4 v[8:9], off
	v_lshl_add_u64 v[8:9], v[10:11], 0, s[84:85]
	v_add_u32_e32 v10, 0x7000, v85
	s_nop 0
	v_readfirstlane_b32 s14, v10
	s_mov_b32 m0, s14
	s_nop 0
	global_load_lds_dwordx4 v[8:9], off

.LBB0_130:
	s_add_u32 s14, s25, s30
	v_cmp_lt_i32_e32 vcc, -1, v4
	s_addc_u32 s17, s33, s31
	s_and_b64 s[30:31], vcc, exec
	v_lshrrev_b32_e32 v7, 4, v6
	v_and_b32_e32 v9, 7, v6
	s_cselect_b32 s31, s17, 0
	s_cselect_b32 s30, s14, 0
	s_add_u32 s28, s44, s28
	v_bfe_u32 v8, v6, 4, 2
	v_bitop3_b32 v7, v7, v9, 3 bitop3:0x6c
	s_addc_u32 s29, s45, s29
	v_lshlrev_b32_e32 v86, 4, v7
	v_bitop3_b32 v7, v8, v9, 4 bitop3:0x36
	v_and_b32_e32 v4, 15, v6
	v_lshlrev_b32_e32 v87, 4, v7
	v_lshrrev_b32_e32 v7, 1, v6
	s_cmp_lg_u64 s[30:31], 0
	v_and_or_b32 v4, v7, s47, v4
	v_lshl_add_u64 v[8:9], s[30:31], 0, v[148:149]
	s_cselect_b64 s[30:31], -1, 0
	s_lshl_b32 s14, s15, 7
	v_lshlrev_b32_e32 v88, 7, v4
	v_lshlrev_b32_e32 v4, 7, v6
	s_add_i32 s14, s83, s14
	s_mov_b32 s15, s27
	v_and_b32_e32 v89, 0x2780, v4
	v_lshl_add_u64 v[6:7], s[28:29], 0, v[148:149]
	v_lshlrev_b64 v[0:1], 13, v[0:1]
	v_lshlrev_b32_e32 v4, 4, v5
	s_lshl_b64 s[14:15], s[14:15], 13
	v_lshl_add_u64 v[64:65], v[8:9], 0, v[2:3]
	v_lshl_add_u64 v[66:67], v[6:7], 0, v[2:3]
	s_and_b32 s16, s56, 7
	s_lshl_b32 s16, s16, 7
	v_mov_b32_e32 v10, s16
	v_mov_b32_e32 v11, 0
	v_lshl_add_u64 v[64:65], v[64:65], 0, v[10:11]
	v_lshl_add_u64 v[66:67], v[66:67], 0, v[10:11]
	v_lshl_add_u64 v[2:3], v[0:1], 0, s[36:37]
	v_and_b32_e32 v148, 0x70, v4
	v_lshl_add_u64 v[0:1], v[0:1], 0, s[14:15]
	s_mov_b64 s[40:41], 0x40000
	s_mov_b64 s[84:85], 0x80000
	s_mov_b64 s[86:87], 0xc0000
	v_lshl_add_u64 v[2:3], v[2:3], 0, v[148:149]
	v_or_b32_e32 v0, v0, v148
	v_mov_b32_e32 v56, 0
	s_mov_b32 s16, 0
	s_mov_b64 s[28:29], 0
	v_lshl_add_u64 v[68:69], v[64:65], 0, s[40:41]
	v_lshl_add_u64 v[70:71], v[64:65], 0, s[84:85]
	v_lshl_add_u64 v[72:73], v[64:65], 0, s[86:87]
	v_lshl_add_u64 v[74:75], v[66:67], 0, s[40:41]
	v_lshl_add_u64 v[76:77], v[66:67], 0, s[84:85]
	v_lshl_add_u64 v[78:79], v[66:67], 0, s[86:87]
	v_lshl_add_u64 v[80:81], s[10:11], 0, v[2:3]
	v_lshl_add_u64 v[82:83], s[10:11], 0, v[0:1]
	s_mov_b32 s17, 0
	v_mov_b32_e32 v57, v56
	v_mov_b32_e32 v58, v56
	v_mov_b32_e32 v59, v56
	v_mov_b32_e32 v0, v56
	v_mov_b32_e32 v1, v56
	v_mov_b32_e32 v2, v56
	v_mov_b32_e32 v3, v56
	v_mov_b32_e32 v4, v56
	v_mov_b32_e32 v5, v56
	v_mov_b32_e32 v6, v56
	v_mov_b32_e32 v7, v56
	v_mov_b32_e32 v8, v56
	v_mov_b32_e32 v9, v56
	v_mov_b32_e32 v10, v56
	v_mov_b32_e32 v11, v56
	v_mov_b32_e32 v12, v56
	v_mov_b32_e32 v13, v56
	v_mov_b32_e32 v14, v56
	v_mov_b32_e32 v15, v56
	v_mov_b32_e32 v16, v56
	v_mov_b32_e32 v17, v56
	v_mov_b32_e32 v18, v56
	v_mov_b32_e32 v19, v56
	v_mov_b32_e32 v20, v56
	v_mov_b32_e32 v21, v56
	v_mov_b32_e32 v22, v56
	v_mov_b32_e32 v23, v56
	v_mov_b32_e32 v24, v56
	v_mov_b32_e32 v25, v56
	v_mov_b32_e32 v26, v56
	v_mov_b32_e32 v27, v56
	v_mov_b32_e32 v28, v56
	v_mov_b32_e32 v29, v56
	v_mov_b32_e32 v30, v56
	v_mov_b32_e32 v31, v56
	v_mov_b32_e32 v32, v56
	v_mov_b32_e32 v33, v56
	v_mov_b32_e32 v34, v56
	v_mov_b32_e32 v35, v56
	v_mov_b32_e32 v36, v56
	v_mov_b32_e32 v37, v56
	v_mov_b32_e32 v38, v56
	v_mov_b32_e32 v39, v56
	s_waitcnt vmcnt(0)
	v_mov_b32_e32 v40, v56
	v_mov_b32_e32 v41, v56
	v_mov_b32_e32 v42, v56
	v_mov_b32_e32 v43, v56
	v_mov_b32_e32 v44, v56
	v_mov_b32_e32 v45, v56
	v_mov_b32_e32 v46, v56
	v_mov_b32_e32 v47, v56
	v_mov_b32_e32 v48, v56
	v_mov_b32_e32 v49, v56
	v_mov_b32_e32 v50, v56
	v_mov_b32_e32 v51, v56
	v_mov_b32_e32 v52, v56
	v_mov_b32_e32 v53, v56
	v_mov_b32_e32 v54, v56
	v_mov_b32_e32 v55, v56
	v_mov_b32_e32 v60, v56
	v_mov_b32_e32 v61, v56
	v_mov_b32_e32 v62, v56
	v_mov_b32_e32 v63, v56
	s_branch .LBB0_132

.LBB0_136:
	s_andn2_b64 vcc, exec, s[14:15]
	s_cbranch_vccnz .LBB0_131
	s_add_i32 s14, s16, 0x8000
	s_and_b32 s14, s14, 0x8000
	v_add_u32_e32 v94, s14, v85
	s_lshl_b32 s15, s26, 0
	s_and_b32 s15, s15, 0x380
	v_readfirstlane_b32 s14, v94
	s_mov_b32 m0, s14
	s_add_u32 s14, s15, s28
	s_add_u32 s14, s14, 0x80
	s_and_b32 s14, s14, 0x1fff
	s_add_u32 s14, s14, 0x1201000
	s_mov_b32 s15, 0
	v_lshl_add_u64 v[92:93], v[82:83], 0, s[14:15]
	s_sub_u32 s14, s14, 0x800000
	v_lshl_add_u64 v[90:91], v[80:81], 0, s[14:15]
	global_load_lds_dwordx4 v[92:93], off
	s_add_u32 m0, m0, 0x1000
	v_lshl_add_u64 v[92:93], v[92:93], 0, s[40:41]
	global_load_lds_dwordx4 v[92:93], off
	s_add_u32 m0, m0, 0x1000
	v_lshl_add_u64 v[92:93], v[92:93], 0, s[40:41]
	global_load_lds_dwordx4 v[92:93], off
	s_add_u32 m0, m0, 0x1000
	v_lshl_add_u64 v[92:93], v[92:93], 0, s[40:41]
	global_load_lds_dwordx4 v[92:93], off
	s_add_u32 m0, m0, 0x1000
	s_nop 0
	global_load_lds_dwordx4 v[90:91], off
	s_add_u32 m0, m0, 0x1000
	v_lshl_add_u64 v[90:91], v[90:91], 0, s[40:41]
	global_load_lds_dwordx4 v[90:91], off
	s_add_u32 m0, m0, 0x1000
	v_lshl_add_u64 v[90:91], v[90:91], 0, s[40:41]
	global_load_lds_dwordx4 v[90:91], off
	s_add_u32 m0, m0, 0x1000
	v_lshl_add_u64 v[90:91], v[90:91], 0, s[40:41]
	global_load_lds_dwordx4 v[90:91], off
	s_branch .LBB0_131
